# v28 + nt hint on phase-0 stores of transposed weights that are first used from phase 4 on
# baseline (speedup 1.0000x reference)
; __device__ __forceinline__ unsigned pk_bf16(float lo, float hi) { const f32x2 v = {lo, hi}; return __builtin_bit_cast(unsigned, __builtin_convertvector(v, b16x2)); }
; __device__ __forceinline__ void transpose_tile(const float* __restrict__ src, int K, int N, bf16_t* __restrict__ dst, int ldd, int koff, int mode, int tile) {
;     float* scr = (float*)smem;
;     const int ntn = N / 128, kb = tile / ntn, nb = tile % ntn, k0 = kb * 64, n0 = nb * 128, tid = threadIdx.x;
;     f32x4 v[4];
; #pragma unroll
;     for (int i = 0; i < 4; ++i) { const int idx = tid + 512 * i, kk = idx >> 5, n4 = idx & 31; v[i] = *(const f32x4*)(src + (size_t)(k0 + kk) * N + n0 + n4 * 4); }
; #pragma unroll
;     for (int i = 0; i < 4; ++i) { const int idx = tid + 512 * i, kk = idx >> 5, n4 = idx & 31;
; #pragma unroll
;         for (int c = 0; c < 4; ++c) scr[kk * 129 + n4 * 4 + c] = v[i][c]; }
;     __syncthreads();
; #pragma unroll
;     for (int i = 0; i < 2; ++i) {
;         const int o = tid + 512 * i, n = o >> 3, kc = (o & 7) * 8;
;         u32x4 w;
;         w.x = pk_bf16(scr[(kc + 0) * 129 + n], scr[(kc + 1) * 129 + n]); w.y = pk_bf16(scr[(kc + 2) * 129 + n], scr[(kc + 3) * 129 + n]);
;         w.z = pk_bf16(scr[(kc + 4) * 129 + n], scr[(kc + 5) * 129 + n]); w.w = pk_bf16(scr[(kc + 6) * 129 + n], scr[(kc + 7) * 129 + n]);
;         const int f = n0 + n;
;         const int drow = mode == 0 ? f : ((f >> 7) * 256 + (mode == 2 ? 128 : 0) + (f & 127));
;         *(u32x4*)(dst + (size_t)drow * ldd + koff + k0 + kc) = w;
;     }
;     __syncthreads();
; }
; __device__ __forceinline__ void phase0(const Params& p) {
;     ...
;             if (r < J6) { transpose_tile(p.in[23], DFF, D, (bf16_t*)(ws + WS_WD), DFF, 0, 0, r); continue; } r -= J6;
.LBB0_65:
	s_andn2_b64 vcc, exec, s[4:5]
	s_cbranch_vccnz .LBB0_67
	s_lshl_b32 s0, s11, 3
	s_and_b32 s0, s0, 0x7fc0
	s_add_i32 s0, s0, 0xac80
	s_and_b32 s4, s0, 0xffc0
	s_lshl_b32 s0, s11, 7
	s_and_b32 s5, s0, 0x380
	s_lshl_b32 s0, s5, 2
	v_or_b32_e32 v0, s4, v165
	v_lshl_add_u64 v[12:13], v[110:111], 0, s[0:1]
	v_lshlrev_b32_e32 v82, 12, v0
	v_or_b32_e32 v0, s4, v81
	v_lshl_add_u64 v[8:9], v[12:13], 0, v[82:83]
	v_lshlrev_b32_e32 v82, 12, v0
	v_lshl_add_u64 v[10:11], v[12:13], 0, v[82:83]
	global_load_dwordx4 v[0:3], v[8:9], off nt
	global_load_dwordx4 v[4:7], v[10:11], off nt
	v_or_b32_e32 v8, s4, v158
	v_lshlrev_b32_e32 v82, 12, v8
	v_lshl_add_u64 v[8:9], v[12:13], 0, v[82:83]
	global_load_dwordx4 v[8:11], v[8:9], off nt
	v_add_lshl_u32 v82, v127, s4, 12
	v_lshl_add_u64 v[12:13], v[12:13], 0, v[82:83]
	global_load_dwordx4 v[12:15], v[12:13], off nt
	v_add_u32_e32 v20, v129, v159
	v_add_u32_e32 v21, v129, v160
	v_add_u32_e32 v22, v129, v161
	v_add_u32_e32 v23, 0x400, v131
	v_add_u32_e32 v24, 0x800, v131
	v_add_u32_e32 v25, 0xc00, v131
	v_add_u32_e32 v26, 0x400, v152
	v_add_u32_e32 v27, 0x800, v152
	v_add_u32_e32 v28, 0xc00, v152
	v_add_u32_e32 v29, 0x4080, v20
	v_add_u32_e32 v30, 0x4088, v20
	v_or_b32_e32 v16, s5, v153
	v_add_u32_e32 v17, s5, v135
	v_mul_u32_u24_e32 v18, 0xb00, v16
	s_lshl_b32 s0, s4, 1
	v_mul_u32_u24_e32 v31, 0xb00, v17
	v_lshl_add_u64 v[16:17], v[92:93], 0, s[0:1]
	v_lshlrev_b32_e32 v82, 1, v18
	v_lshl_add_u64 v[18:19], v[16:17], 0, v[82:83]
	v_lshlrev_b32_e32 v82, 1, v31
	v_lshl_add_u64 v[16:17], v[16:17], 0, v[82:83]
	s_waitcnt vmcnt(3)
	ds_write2_b32 v20, v0, v1 offset1:1
	ds_write2_b32 v20, v2, v3 offset0:2 offset1:3
	s_waitcnt vmcnt(2)
	ds_write2_b32 v21, v4, v5 offset1:1
	ds_write2_b32 v21, v6, v7 offset0:2 offset1:3
	s_waitcnt vmcnt(1)
	ds_write2_b32 v29, v8, v9 offset1:1
	ds_write2_b32 v30, v10, v11 offset1:1
	s_waitcnt vmcnt(0)
	ds_write2_b32 v22, v12, v13 offset1:1
	ds_write2_b32 v22, v14, v15 offset0:2 offset1:3
	s_waitcnt lgkmcnt(0)
	s_barrier
	ds_read2_b32 v[0:1], v131 offset1:129
	ds_read2_b32 v[2:3], v23 offset0:2 offset1:131
	ds_read2_b32 v[4:5], v24 offset0:4 offset1:133
	ds_read2_b32 v[6:7], v25 offset0:6 offset1:135
	ds_read2_b32 v[8:9], v152 offset1:129
	ds_read2_b32 v[10:11], v26 offset0:2 offset1:131
	ds_read2_b32 v[12:13], v27 offset0:4 offset1:133
	ds_read2_b32 v[14:15], v28 offset0:6 offset1:135
	s_waitcnt lgkmcnt(7)
	v_cvt_pk_bf16_f32 v0, v0, v1
	s_waitcnt lgkmcnt(6)
	v_cvt_pk_bf16_f32 v1, v2, v3
	s_waitcnt lgkmcnt(5)
	v_cvt_pk_bf16_f32 v2, v4, v5
	s_waitcnt lgkmcnt(4)
	v_cvt_pk_bf16_f32 v3, v6, v7
	s_waitcnt lgkmcnt(3)
	v_cvt_pk_bf16_f32 v4, v8, v9
	s_waitcnt lgkmcnt(2)
	v_cvt_pk_bf16_f32 v5, v10, v11
	s_waitcnt lgkmcnt(1)
	v_cvt_pk_bf16_f32 v6, v12, v13
	s_waitcnt lgkmcnt(0)
	v_cvt_pk_bf16_f32 v7, v14, v15
	global_store_dwordx4 v[18:19], v[0:3], off nt
	global_store_dwordx4 v[16:17], v[4:7], off nt
	s_barrier

; __device__ __forceinline__ unsigned pk_bf16(float lo, float hi) { const f32x2 v = {lo, hi}; return __builtin_bit_cast(unsigned, __builtin_convertvector(v, b16x2)); }
; __device__ __forceinline__ void transpose_tile(const float* __restrict__ src, int K, int N, bf16_t* __restrict__ dst, int ldd, int koff, int mode, int tile) {
;     float* scr = (float*)smem;
;     const int ntn = N / 128, kb = tile / ntn, nb = tile % ntn, k0 = kb * 64, n0 = nb * 128, tid = threadIdx.x;
;     f32x4 v[4];
; #pragma unroll
;     for (int i = 0; i < 4; ++i) { const int idx = tid + 512 * i, kk = idx >> 5, n4 = idx & 31; v[i] = *(const f32x4*)(src + (size_t)(k0 + kk) * N + n0 + n4 * 4); }
; #pragma unroll
;     for (int i = 0; i < 4; ++i) { const int idx = tid + 512 * i, kk = idx >> 5, n4 = idx & 31;
; #pragma unroll
;         for (int c = 0; c < 4; ++c) scr[kk * 129 + n4 * 4 + c] = v[i][c]; }
;     __syncthreads();
; #pragma unroll
;     for (int i = 0; i < 2; ++i) {
;         const int o = tid + 512 * i, n = o >> 3, kc = (o & 7) * 8;
;         u32x4 w;
;         w.x = pk_bf16(scr[(kc + 0) * 129 + n], scr[(kc + 1) * 129 + n]); w.y = pk_bf16(scr[(kc + 2) * 129 + n], scr[(kc + 3) * 129 + n]);
;         w.z = pk_bf16(scr[(kc + 4) * 129 + n], scr[(kc + 5) * 129 + n]); w.w = pk_bf16(scr[(kc + 6) * 129 + n], scr[(kc + 7) * 129 + n]);
;         const int f = n0 + n;
;         const int drow = mode == 0 ? f : ((f >> 7) * 256 + (mode == 2 ? 128 : 0) + (f & 127));
;         *(u32x4*)(dst + (size_t)drow * ldd + koff + k0 + kc) = w;
;     }
;     __syncthreads();
; }
; __device__ __forceinline__ void phase0(const Params& p) {
;     ...
;             if (r < J4) { transpose_tile(p.in[22], D, DFF, (bf16_t*)(ws + WS_WGU), D, 0, 2, r); continue; } r -= J4;
.LBB0_68:
	s_andn2_b64 vcc, exec, s[4:5]
	s_cbranch_vccnz .LBB0_70
	s_add_i32 s0, s11, 0xf6f0
	s_and_b32 s4, s0, 0xffff
	s_mul_i32 s4, s4, 0xba2f
	s_lshr_b32 s5, s4, 20
	s_mul_i32 s5, s5, 22
	s_lshr_b32 s4, s4, 14
	s_sub_i32 s0, s0, s5
	s_and_b32 s4, s4, 0xffc0
	s_lshl_b32 s0, s0, 7
	v_or_b32_e32 v0, s4, v165
	s_and_b32 s5, s0, 0xff80
	v_mul_u32_u24_e32 v0, 0xb00, v0
	s_lshl_b32 s0, s5, 2
	v_lshlrev_b32_e32 v82, 2, v0
	v_or_b32_e32 v0, s4, v81
	v_lshl_add_u64 v[12:13], v[112:113], 0, s[0:1]
	v_mul_u32_u24_e32 v0, 0xb00, v0
	v_lshl_add_u64 v[8:9], v[12:13], 0, v[82:83]
	v_lshlrev_b32_e32 v82, 2, v0
	v_lshl_add_u64 v[10:11], v[12:13], 0, v[82:83]
	global_load_dwordx4 v[0:3], v[8:9], off nt
	global_load_dwordx4 v[4:7], v[10:11], off nt
	v_or_b32_e32 v8, s4, v158
	v_mul_u32_u24_e32 v8, 0xb00, v8
	v_lshlrev_b32_e32 v82, 2, v8
	v_add_u32_e32 v14, s4, v127
	v_lshl_add_u64 v[8:9], v[12:13], 0, v[82:83]
	v_mul_u32_u24_e32 v14, 0xb00, v14
	global_load_dwordx4 v[8:11], v[8:9], off nt
	v_lshlrev_b32_e32 v82, 2, v14
	v_lshl_add_u64 v[12:13], v[12:13], 0, v[82:83]
	global_load_dwordx4 v[12:15], v[12:13], off nt
	v_add_u32_e32 v20, v129, v159
	v_add_u32_e32 v21, v129, v160
	v_add_u32_e32 v22, v129, v161
	v_add_u32_e32 v23, 0x400, v131
	v_add_u32_e32 v24, 0x800, v131
	v_add_u32_e32 v25, 0xc00, v131
	v_add_u32_e32 v26, 0x400, v152
	v_add_u32_e32 v27, 0x800, v152
	v_add_u32_e32 v28, 0xc00, v152
	v_add_u32_e32 v29, 0x4080, v20
	v_add_u32_e32 v30, 0x4088, v20
	v_add_lshl_u32 v16, v135, s5, 1
	s_lshl_b32 s0, s4, 1
	v_and_or_b32 v31, v16, s10, v135
	v_lshl_add_u64 v[16:17], v[94:95], 0, s[0:1]
	v_lshl_or_b32 v82, s5, 12, v157
	v_lshl_add_u64 v[18:19], v[16:17], 0, v[82:83]
	v_lshl_or_b32 v82, v31, 11, v163
	v_lshl_add_u64 v[16:17], v[16:17], 0, v[82:83]
	s_waitcnt vmcnt(3)
	ds_write2_b32 v20, v0, v1 offset1:1
	ds_write2_b32 v20, v2, v3 offset0:2 offset1:3
	s_waitcnt vmcnt(2)
	ds_write2_b32 v21, v4, v5 offset1:1
	ds_write2_b32 v21, v6, v7 offset0:2 offset1:3
	s_waitcnt vmcnt(1)
	ds_write2_b32 v29, v8, v9 offset1:1
	ds_write2_b32 v30, v10, v11 offset1:1
	s_waitcnt vmcnt(0)
	ds_write2_b32 v22, v12, v13 offset1:1
	ds_write2_b32 v22, v14, v15 offset0:2 offset1:3
	s_waitcnt lgkmcnt(0)
	s_barrier
	ds_read2_b32 v[0:1], v131 offset1:129
	ds_read2_b32 v[2:3], v23 offset0:2 offset1:131
	ds_read2_b32 v[4:5], v24 offset0:4 offset1:133
	ds_read2_b32 v[6:7], v25 offset0:6 offset1:135
	ds_read2_b32 v[8:9], v152 offset1:129
	ds_read2_b32 v[10:11], v26 offset0:2 offset1:131
	ds_read2_b32 v[12:13], v27 offset0:4 offset1:133
	ds_read2_b32 v[14:15], v28 offset0:6 offset1:135
	s_waitcnt lgkmcnt(7)
	v_cvt_pk_bf16_f32 v0, v0, v1
	s_waitcnt lgkmcnt(6)
	v_cvt_pk_bf16_f32 v1, v2, v3
	s_waitcnt lgkmcnt(5)
	v_cvt_pk_bf16_f32 v2, v4, v5
	s_waitcnt lgkmcnt(4)
	v_cvt_pk_bf16_f32 v3, v6, v7
	s_waitcnt lgkmcnt(3)
	v_cvt_pk_bf16_f32 v4, v8, v9
	s_waitcnt lgkmcnt(2)
	v_cvt_pk_bf16_f32 v5, v10, v11
	s_waitcnt lgkmcnt(1)
	v_cvt_pk_bf16_f32 v6, v12, v13
	s_waitcnt lgkmcnt(0)
	v_cvt_pk_bf16_f32 v7, v14, v15
	global_store_dwordx4 v[18:19], v[0:3], off nt
	global_store_dwordx4 v[16:17], v[4:7], off nt
	s_barrier

; __device__ __forceinline__ unsigned pk_bf16(float lo, float hi) { const f32x2 v = {lo, hi}; return __builtin_bit_cast(unsigned, __builtin_convertvector(v, b16x2)); }
; __device__ __forceinline__ void transpose_tile(const float* __restrict__ src, int K, int N, bf16_t* __restrict__ dst, int ldd, int koff, int mode, int tile) {
;     float* scr = (float*)smem;
;     const int ntn = N / 128, kb = tile / ntn, nb = tile % ntn, k0 = kb * 64, n0 = nb * 128, tid = threadIdx.x;
;     f32x4 v[4];
; #pragma unroll
;     for (int i = 0; i < 4; ++i) { const int idx = tid + 512 * i, kk = idx >> 5, n4 = idx & 31; v[i] = *(const f32x4*)(src + (size_t)(k0 + kk) * N + n0 + n4 * 4); }
; #pragma unroll
;     for (int i = 0; i < 4; ++i) { const int idx = tid + 512 * i, kk = idx >> 5, n4 = idx & 31;
; #pragma unroll
;         for (int c = 0; c < 4; ++c) scr[kk * 129 + n4 * 4 + c] = v[i][c]; }
;     __syncthreads();
; #pragma unroll
;     for (int i = 0; i < 2; ++i) {
;         const int o = tid + 512 * i, n = o >> 3, kc = (o & 7) * 8;
;         u32x4 w;
;         w.x = pk_bf16(scr[(kc + 0) * 129 + n], scr[(kc + 1) * 129 + n]); w.y = pk_bf16(scr[(kc + 2) * 129 + n], scr[(kc + 3) * 129 + n]);
;         w.z = pk_bf16(scr[(kc + 4) * 129 + n], scr[(kc + 5) * 129 + n]); w.w = pk_bf16(scr[(kc + 6) * 129 + n], scr[(kc + 7) * 129 + n]);
;         const int f = n0 + n;
;         const int drow = mode == 0 ? f : ((f >> 7) * 256 + (mode == 2 ? 128 : 0) + (f & 127));
;         *(u32x4*)(dst + (size_t)drow * ldd + koff + k0 + kc) = w;
;     }
;     __syncthreads();
; }
; __device__ __forceinline__ void phase0(const Params& p) {
;     ...
;             if (r < J4) { transpose_tile(p.in[21], D, DFF, (bf16_t*)(ws + WS_WGU), D, 0, 1, r); continue; } r -= J4;
.LBB0_71:
	s_andn2_b64 vcc, exec, s[4:5]
	s_cbranch_vccnz .LBB0_73
	s_add_i32 s0, s11, 0xf850
	s_and_b32 s4, s0, 0xffff
	s_mul_i32 s4, s4, 0xba2f
	s_lshr_b32 s5, s4, 20
	s_mul_i32 s5, s5, 22
	s_lshr_b32 s4, s4, 14
	s_sub_i32 s0, s0, s5
	s_and_b32 s4, s4, 0xffc0
	s_lshl_b32 s0, s0, 7
	v_or_b32_e32 v0, s4, v165
	s_and_b32 s5, s0, 0xff80
	v_mul_u32_u24_e32 v0, 0xb00, v0
	s_lshl_b32 s0, s5, 2
	v_lshlrev_b32_e32 v82, 2, v0
	v_or_b32_e32 v0, s4, v81
	v_lshl_add_u64 v[12:13], v[114:115], 0, s[0:1]
	v_mul_u32_u24_e32 v0, 0xb00, v0
	v_lshl_add_u64 v[8:9], v[12:13], 0, v[82:83]
	v_lshlrev_b32_e32 v82, 2, v0
	v_lshl_add_u64 v[10:11], v[12:13], 0, v[82:83]
	global_load_dwordx4 v[0:3], v[8:9], off nt
	global_load_dwordx4 v[4:7], v[10:11], off nt
	v_or_b32_e32 v8, s4, v158
	v_mul_u32_u24_e32 v8, 0xb00, v8
	v_lshlrev_b32_e32 v82, 2, v8
	v_add_u32_e32 v14, s4, v127
	v_lshl_add_u64 v[8:9], v[12:13], 0, v[82:83]
	v_mul_u32_u24_e32 v14, 0xb00, v14
	global_load_dwordx4 v[8:11], v[8:9], off nt
	v_lshlrev_b32_e32 v82, 2, v14
	v_lshl_add_u64 v[12:13], v[12:13], 0, v[82:83]
	global_load_dwordx4 v[12:15], v[12:13], off nt
	v_add_u32_e32 v20, v129, v159
	v_add_u32_e32 v21, v129, v160
	v_add_u32_e32 v22, v129, v161
	v_add_u32_e32 v23, 0x400, v131
	v_add_u32_e32 v24, 0x800, v131
	v_add_u32_e32 v25, 0xc00, v131
	v_add_u32_e32 v26, 0x400, v152
	v_add_u32_e32 v27, 0x800, v152
	v_add_u32_e32 v28, 0xc00, v152
	v_add_u32_e32 v29, 0x4080, v20
	v_add_u32_e32 v30, 0x4088, v20
	v_lshlrev_b32_e32 v18, 1, v154
	v_add_lshl_u32 v16, v135, s5, 1
	s_lshl_b32 s0, s4, 1
	v_and_or_b32 v31, v16, s10, v155
	v_lshl_add_u64 v[16:17], v[94:95], 0, s[0:1]
	v_lshl_or_b32 v82, s5, 12, v18
	v_lshl_add_u64 v[18:19], v[16:17], 0, v[82:83]
	v_lshlrev_b32_e32 v82, 11, v31
	v_lshl_add_u64 v[16:17], v[16:17], 0, v[82:83]
	s_waitcnt vmcnt(3)
	ds_write2_b32 v20, v0, v1 offset1:1
	ds_write2_b32 v20, v2, v3 offset0:2 offset1:3
	s_waitcnt vmcnt(2)
	ds_write2_b32 v21, v4, v5 offset1:1
	ds_write2_b32 v21, v6, v7 offset0:2 offset1:3
	s_waitcnt vmcnt(1)
	ds_write2_b32 v29, v8, v9 offset1:1
	ds_write2_b32 v30, v10, v11 offset1:1
	s_waitcnt vmcnt(0)
	ds_write2_b32 v22, v12, v13 offset1:1
	ds_write2_b32 v22, v14, v15 offset0:2 offset1:3
	s_waitcnt lgkmcnt(0)
	s_barrier
	ds_read2_b32 v[0:1], v131 offset1:129
	ds_read2_b32 v[2:3], v23 offset0:2 offset1:131
	ds_read2_b32 v[4:5], v24 offset0:4 offset1:133
	ds_read2_b32 v[6:7], v25 offset0:6 offset1:135
	ds_read2_b32 v[8:9], v152 offset1:129
	ds_read2_b32 v[10:11], v26 offset0:2 offset1:131
	ds_read2_b32 v[12:13], v27 offset0:4 offset1:133
	ds_read2_b32 v[14:15], v28 offset0:6 offset1:135
	s_waitcnt lgkmcnt(7)
	v_cvt_pk_bf16_f32 v0, v0, v1
	s_waitcnt lgkmcnt(6)
	v_cvt_pk_bf16_f32 v1, v2, v3
	s_waitcnt lgkmcnt(5)
	v_cvt_pk_bf16_f32 v2, v4, v5
	s_waitcnt lgkmcnt(4)
	v_cvt_pk_bf16_f32 v3, v6, v7
	s_waitcnt lgkmcnt(3)
	v_cvt_pk_bf16_f32 v4, v8, v9
	s_waitcnt lgkmcnt(2)
	v_cvt_pk_bf16_f32 v5, v10, v11
	s_waitcnt lgkmcnt(1)
	v_cvt_pk_bf16_f32 v6, v12, v13
	s_waitcnt lgkmcnt(0)
	v_cvt_pk_bf16_f32 v7, v14, v15
	global_store_dwordx4 v[18:19], v[0:3], off nt
	global_store_dwordx4 v[16:17], v[4:7], off nt
	s_barrier

; __device__ __forceinline__ unsigned pk_bf16(float lo, float hi) { const f32x2 v = {lo, hi}; return __builtin_bit_cast(unsigned, __builtin_convertvector(v, b16x2)); }
; __device__ __forceinline__ void transpose_tile(const float* __restrict__ src, int K, int N, bf16_t* __restrict__ dst, int ldd, int koff, int mode, int tile) {
;     float* scr = (float*)smem;
;     const int ntn = N / 128, kb = tile / ntn, nb = tile % ntn, k0 = kb * 64, n0 = nb * 128, tid = threadIdx.x;
;     f32x4 v[4];
; #pragma unroll
;     for (int i = 0; i < 4; ++i) { const int idx = tid + 512 * i, kk = idx >> 5, n4 = idx & 31; v[i] = *(const f32x4*)(src + (size_t)(k0 + kk) * N + n0 + n4 * 4); }
; #pragma unroll
;     for (int i = 0; i < 4; ++i) { const int idx = tid + 512 * i, kk = idx >> 5, n4 = idx & 31;
; #pragma unroll
;         for (int c = 0; c < 4; ++c) scr[kk * 129 + n4 * 4 + c] = v[i][c]; }
;     __syncthreads();
; #pragma unroll
;     for (int i = 0; i < 2; ++i) {
;         const int o = tid + 512 * i, n = o >> 3, kc = (o & 7) * 8;
;         u32x4 w;
;         w.x = pk_bf16(scr[(kc + 0) * 129 + n], scr[(kc + 1) * 129 + n]); w.y = pk_bf16(scr[(kc + 2) * 129 + n], scr[(kc + 3) * 129 + n]);
;         w.z = pk_bf16(scr[(kc + 4) * 129 + n], scr[(kc + 5) * 129 + n]); w.w = pk_bf16(scr[(kc + 6) * 129 + n], scr[(kc + 7) * 129 + n]);
;         const int f = n0 + n;
;         const int drow = mode == 0 ? f : ((f >> 7) * 256 + (mode == 2 ? 128 : 0) + (f & 127));
;         *(u32x4*)(dst + (size_t)drow * ldd + koff + k0 + kc) = w;
;     }
;     __syncthreads();
; }
; __device__ __forceinline__ void phase0(const Params& p) {
;     ...
;             if (r < J3) { transpose_tile(p.in[18], D, D, (bf16_t*)(ws + WS_WOUT), D, 0, 0, r); continue; } r -= J3;
.LBB0_74:
	s_andn2_b64 vcc, exec, s[4:5]
	s_cbranch_vccnz .LBB0_76
	s_lshl_b32 s0, s11, 3
	s_add_i32 s0, s0, 0x7fe80
	s_and_b32 s4, s0, 0x7c0
	s_lshl_b32 s0, s11, 7
	s_and_b32 s5, s0, 0x380
	s_lshl_b32 s0, s5, 2
	v_or_b32_e32 v0, s4, v165
	v_lshl_add_u64 v[12:13], v[116:117], 0, s[0:1]
	v_lshlrev_b32_e32 v82, 12, v0
	v_or_b32_e32 v0, s4, v81
	v_lshl_add_u64 v[8:9], v[12:13], 0, v[82:83]
	v_lshlrev_b32_e32 v82, 12, v0
	v_lshl_add_u64 v[10:11], v[12:13], 0, v[82:83]
	global_load_dwordx4 v[0:3], v[8:9], off nt
	global_load_dwordx4 v[4:7], v[10:11], off nt
	v_or_b32_e32 v8, s4, v158
	v_lshlrev_b32_e32 v82, 12, v8
	v_lshl_add_u64 v[8:9], v[12:13], 0, v[82:83]
	global_load_dwordx4 v[8:11], v[8:9], off nt
	v_add_lshl_u32 v82, v127, s4, 12
	v_lshl_add_u64 v[12:13], v[12:13], 0, v[82:83]
	global_load_dwordx4 v[12:15], v[12:13], off nt
	v_add_u32_e32 v20, v129, v159
	v_add_u32_e32 v21, v129, v160
	v_add_u32_e32 v22, v129, v161
	v_add_u32_e32 v23, 0x400, v131
	v_add_u32_e32 v24, 0x800, v131
	v_add_u32_e32 v25, 0xc00, v131
	v_add_u32_e32 v26, 0x400, v152
	v_add_u32_e32 v27, 0x800, v152
	v_add_u32_e32 v28, 0xc00, v152
	v_add_u32_e32 v29, 0x4080, v20
	v_add_u32_e32 v30, 0x4088, v20
	v_or_b32_e32 v18, s5, v153
	s_lshl_b32 s0, s4, 1
	v_lshl_add_u64 v[16:17], v[96:97], 0, s[0:1]
	v_lshlrev_b32_e32 v82, 11, v18
	v_lshl_add_u64 v[18:19], v[16:17], 0, v[82:83]
	v_add_lshl_u32 v82, v135, s5, 11
	v_lshl_add_u64 v[16:17], v[16:17], 0, v[82:83]
	s_waitcnt vmcnt(3)
	ds_write2_b32 v20, v0, v1 offset1:1
	ds_write2_b32 v20, v2, v3 offset0:2 offset1:3
	s_waitcnt vmcnt(2)
	ds_write2_b32 v21, v4, v5 offset1:1
	ds_write2_b32 v21, v6, v7 offset0:2 offset1:3
	s_waitcnt vmcnt(1)
	ds_write2_b32 v29, v8, v9 offset1:1
	ds_write2_b32 v30, v10, v11 offset1:1
	s_waitcnt vmcnt(0)
	ds_write2_b32 v22, v12, v13 offset1:1
	ds_write2_b32 v22, v14, v15 offset0:2 offset1:3
	s_waitcnt lgkmcnt(0)
	s_barrier
	ds_read2_b32 v[0:1], v131 offset1:129
	ds_read2_b32 v[2:3], v23 offset0:2 offset1:131
	ds_read2_b32 v[4:5], v24 offset0:4 offset1:133
	ds_read2_b32 v[6:7], v25 offset0:6 offset1:135
	ds_read2_b32 v[8:9], v152 offset1:129
	ds_read2_b32 v[10:11], v26 offset0:2 offset1:131
	ds_read2_b32 v[12:13], v27 offset0:4 offset1:133
	ds_read2_b32 v[14:15], v28 offset0:6 offset1:135
	s_waitcnt lgkmcnt(7)
	v_cvt_pk_bf16_f32 v0, v0, v1
	s_waitcnt lgkmcnt(6)
	v_cvt_pk_bf16_f32 v1, v2, v3
	s_waitcnt lgkmcnt(5)
	v_cvt_pk_bf16_f32 v2, v4, v5
	s_waitcnt lgkmcnt(4)
	v_cvt_pk_bf16_f32 v3, v6, v7
	s_waitcnt lgkmcnt(3)
	v_cvt_pk_bf16_f32 v4, v8, v9
	s_waitcnt lgkmcnt(2)
	v_cvt_pk_bf16_f32 v5, v10, v11
	s_waitcnt lgkmcnt(1)
	v_cvt_pk_bf16_f32 v6, v12, v13
	s_waitcnt lgkmcnt(0)
	v_cvt_pk_bf16_f32 v7, v14, v15
	global_store_dwordx4 v[18:19], v[0:3], off nt
	global_store_dwordx4 v[16:17], v[4:7], off nt
	s_barrier

; __device__ __forceinline__ unsigned pk_bf16(float lo, float hi) { const f32x2 v = {lo, hi}; return __builtin_bit_cast(unsigned, __builtin_convertvector(v, b16x2)); }
; __device__ __forceinline__ void transpose_tile(const float* __restrict__ src, int K, int N, bf16_t* __restrict__ dst, int ldd, int koff, int mode, int tile) {
;     float* scr = (float*)smem;
;     const int ntn = N / 128, kb = tile / ntn, nb = tile % ntn, k0 = kb * 64, n0 = nb * 128, tid = threadIdx.x;
;     f32x4 v[4];
; #pragma unroll
;     for (int i = 0; i < 4; ++i) { const int idx = tid + 512 * i, kk = idx >> 5, n4 = idx & 31; v[i] = *(const f32x4*)(src + (size_t)(k0 + kk) * N + n0 + n4 * 4); }
; #pragma unroll
;     for (int i = 0; i < 4; ++i) { const int idx = tid + 512 * i, kk = idx >> 5, n4 = idx & 31;
; #pragma unroll
;         for (int c = 0; c < 4; ++c) scr[kk * 129 + n4 * 4 + c] = v[i][c]; }
;     __syncthreads();
; #pragma unroll
;     for (int i = 0; i < 2; ++i) {
;         const int o = tid + 512 * i, n = o >> 3, kc = (o & 7) * 8;
;         u32x4 w;
;         w.x = pk_bf16(scr[(kc + 0) * 129 + n], scr[(kc + 1) * 129 + n]); w.y = pk_bf16(scr[(kc + 2) * 129 + n], scr[(kc + 3) * 129 + n]);
;         w.z = pk_bf16(scr[(kc + 4) * 129 + n], scr[(kc + 5) * 129 + n]); w.w = pk_bf16(scr[(kc + 6) * 129 + n], scr[(kc + 7) * 129 + n]);
;         const int f = n0 + n;
;         const int drow = mode == 0 ? f : ((f >> 7) * 256 + (mode == 2 ? 128 : 0) + (f & 127));
;         *(u32x4*)(dst + (size_t)drow * ldd + koff + k0 + kc) = w;
;     }
;     __syncthreads();
; }
; __device__ __forceinline__ void phase0(const Params& p) {
;     ...
;             if (r < J1) { transpose_tile(p.in[17], 512, D, (bf16_t*)(ws + WS_WRW), 512, 0, 0, r); continue; } r -= J1;
.LBB0_77:
	s_andn2_b64 vcc, exec, s[4:5]
	s_cbranch_vccnz .LBB0_79
	s_lshl_b32 s0, s11, 3
	s_addk_i32 s0, 0x80
	s_and_b32 s4, s0, 0x7c0
	s_lshl_b32 s0, s11, 7
	s_and_b32 s5, s0, 0x380
	s_lshl_b32 s0, s5, 2
	v_or_b32_e32 v0, s4, v165
	v_lshl_add_u64 v[12:13], v[118:119], 0, s[0:1]
	v_lshlrev_b32_e32 v82, 12, v0
	v_or_b32_e32 v0, s4, v81
	v_lshl_add_u64 v[8:9], v[12:13], 0, v[82:83]
	v_lshlrev_b32_e32 v82, 12, v0
	v_lshl_add_u64 v[10:11], v[12:13], 0, v[82:83]
	global_load_dwordx4 v[0:3], v[8:9], off nt
	global_load_dwordx4 v[4:7], v[10:11], off nt
	v_or_b32_e32 v8, s4, v158
	v_lshlrev_b32_e32 v82, 12, v8
	v_lshl_add_u64 v[8:9], v[12:13], 0, v[82:83]
	global_load_dwordx4 v[8:11], v[8:9], off nt
	v_add_lshl_u32 v82, v127, s4, 12
	v_lshl_add_u64 v[12:13], v[12:13], 0, v[82:83]
	global_load_dwordx4 v[12:15], v[12:13], off nt
	v_add_u32_e32 v20, v129, v159
	v_add_u32_e32 v21, v129, v160
	v_add_u32_e32 v22, v129, v161
	v_add_u32_e32 v23, 0x400, v131
	v_add_u32_e32 v24, 0x800, v131
	v_add_u32_e32 v25, 0xc00, v131
	v_add_u32_e32 v26, 0x400, v152
	v_add_u32_e32 v27, 0x800, v152
	v_add_u32_e32 v28, 0xc00, v152
	v_add_u32_e32 v29, 0x4080, v20
	v_add_u32_e32 v30, 0x4088, v20
	v_or_b32_e32 v18, s5, v153
	s_lshl_b32 s0, s4, 1
	v_lshl_add_u64 v[16:17], v[98:99], 0, s[0:1]
	v_lshlrev_b32_e32 v82, 10, v18
	v_lshl_add_u64 v[18:19], v[16:17], 0, v[82:83]
	v_add_lshl_u32 v82, v135, s5, 10
	v_lshl_add_u64 v[16:17], v[16:17], 0, v[82:83]
	s_waitcnt vmcnt(3)
	ds_write2_b32 v20, v0, v1 offset1:1
	ds_write2_b32 v20, v2, v3 offset0:2 offset1:3
	s_waitcnt vmcnt(2)
	ds_write2_b32 v21, v4, v5 offset1:1
	ds_write2_b32 v21, v6, v7 offset0:2 offset1:3
	s_waitcnt vmcnt(1)
	ds_write2_b32 v29, v8, v9 offset1:1
	ds_write2_b32 v30, v10, v11 offset1:1
	s_waitcnt vmcnt(0)
	ds_write2_b32 v22, v12, v13 offset1:1
	ds_write2_b32 v22, v14, v15 offset0:2 offset1:3
	s_waitcnt lgkmcnt(0)
	s_barrier
	ds_read2_b32 v[0:1], v131 offset1:129
	ds_read2_b32 v[2:3], v23 offset0:2 offset1:131
	ds_read2_b32 v[4:5], v24 offset0:4 offset1:133
	ds_read2_b32 v[6:7], v25 offset0:6 offset1:135
	ds_read2_b32 v[8:9], v152 offset1:129
	ds_read2_b32 v[10:11], v26 offset0:2 offset1:131
	ds_read2_b32 v[12:13], v27 offset0:4 offset1:133
	ds_read2_b32 v[14:15], v28 offset0:6 offset1:135
	s_waitcnt lgkmcnt(7)
	v_cvt_pk_bf16_f32 v0, v0, v1
	s_waitcnt lgkmcnt(6)
	v_cvt_pk_bf16_f32 v1, v2, v3
	s_waitcnt lgkmcnt(5)
	v_cvt_pk_bf16_f32 v2, v4, v5
	s_waitcnt lgkmcnt(4)
	v_cvt_pk_bf16_f32 v3, v6, v7
	s_waitcnt lgkmcnt(3)
	v_cvt_pk_bf16_f32 v4, v8, v9
	s_waitcnt lgkmcnt(2)
	v_cvt_pk_bf16_f32 v5, v10, v11
	s_waitcnt lgkmcnt(1)
	v_cvt_pk_bf16_f32 v6, v12, v13
	s_waitcnt lgkmcnt(0)
	v_cvt_pk_bf16_f32 v7, v14, v15
	global_store_dwordx4 v[18:19], v[0:3], off nt
	global_store_dwordx4 v[16:17], v[4:7], off nt
	s_barrier

; __device__ __forceinline__ unsigned pk_bf16(float lo, float hi) { const f32x2 v = {lo, hi}; return __builtin_bit_cast(unsigned, __builtin_convertvector(v, b16x2)); }
; __device__ __forceinline__ void transpose_tile(const float* __restrict__ src, int K, int N, bf16_t* __restrict__ dst, int ldd, int koff, int mode, int tile) {
;     float* scr = (float*)smem;
;     const int ntn = N / 128, kb = tile / ntn, nb = tile % ntn, k0 = kb * 64, n0 = nb * 128, tid = threadIdx.x;
;     f32x4 v[4];
; #pragma unroll
;     for (int i = 0; i < 4; ++i) { const int idx = tid + 512 * i, kk = idx >> 5, n4 = idx & 31; v[i] = *(const f32x4*)(src + (size_t)(k0 + kk) * N + n0 + n4 * 4); }
; #pragma unroll
;     for (int i = 0; i < 4; ++i) { const int idx = tid + 512 * i, kk = idx >> 5, n4 = idx & 31;
; #pragma unroll
;         for (int c = 0; c < 4; ++c) scr[kk * 129 + n4 * 4 + c] = v[i][c]; }
;     __syncthreads();
; #pragma unroll
;     for (int i = 0; i < 2; ++i) {
;         const int o = tid + 512 * i, n = o >> 3, kc = (o & 7) * 8;
;         u32x4 w;
;         w.x = pk_bf16(scr[(kc + 0) * 129 + n], scr[(kc + 1) * 129 + n]); w.y = pk_bf16(scr[(kc + 2) * 129 + n], scr[(kc + 3) * 129 + n]);
;         w.z = pk_bf16(scr[(kc + 4) * 129 + n], scr[(kc + 5) * 129 + n]); w.w = pk_bf16(scr[(kc + 6) * 129 + n], scr[(kc + 7) * 129 + n]);
;         const int f = n0 + n;
;         const int drow = mode == 0 ? f : ((f >> 7) * 256 + (mode == 2 ? 128 : 0) + (f & 127));
;         *(u32x4*)(dst + (size_t)drow * ldd + koff + k0 + kc) = w;
;     }
;     __syncthreads();
; }
; __device__ __forceinline__ void phase0(const Params& p) {
;     ...
;             if (r < J1) { transpose_tile(p.in[16], 512, D, (bf16_t*)(ws + WS_WSB), 512, 0, 0, r); continue; } r -= J1;
.LBB0_80:
	s_andn2_b64 vcc, exec, s[4:5]
	s_cbranch_vccnz .LBB0_82
	s_lshl_b32 s0, s11, 3
	s_addk_i32 s0, 0x280
	s_and_b32 s4, s0, 0x7c0
	s_lshl_b32 s0, s11, 7
	s_and_b32 s5, s0, 0x380
	s_lshl_b32 s0, s5, 2
	v_or_b32_e32 v0, s4, v165
	v_lshl_add_u64 v[12:13], v[120:121], 0, s[0:1]
	v_lshlrev_b32_e32 v82, 12, v0
	v_or_b32_e32 v0, s4, v81
	v_lshl_add_u64 v[8:9], v[12:13], 0, v[82:83]
	v_lshlrev_b32_e32 v82, 12, v0
	v_lshl_add_u64 v[10:11], v[12:13], 0, v[82:83]
	global_load_dwordx4 v[0:3], v[8:9], off nt
	global_load_dwordx4 v[4:7], v[10:11], off nt
	v_or_b32_e32 v8, s4, v158
	v_lshlrev_b32_e32 v82, 12, v8
	v_lshl_add_u64 v[8:9], v[12:13], 0, v[82:83]
	global_load_dwordx4 v[8:11], v[8:9], off nt
	v_add_lshl_u32 v82, v127, s4, 12
	v_lshl_add_u64 v[12:13], v[12:13], 0, v[82:83]
	global_load_dwordx4 v[12:15], v[12:13], off nt
	v_add_u32_e32 v20, v129, v159
	v_add_u32_e32 v21, v129, v160
	v_add_u32_e32 v22, v129, v161
	v_add_u32_e32 v23, 0x400, v131
	v_add_u32_e32 v24, 0x800, v131
	v_add_u32_e32 v25, 0xc00, v131
	v_add_u32_e32 v26, 0x400, v152
	v_add_u32_e32 v27, 0x800, v152
	v_add_u32_e32 v28, 0xc00, v152
	v_add_u32_e32 v29, 0x4080, v20
	v_add_u32_e32 v30, 0x4088, v20
	v_or_b32_e32 v18, s5, v153
	s_lshl_b32 s0, s4, 1
	v_lshl_add_u64 v[16:17], v[100:101], 0, s[0:1]
	v_lshlrev_b32_e32 v82, 10, v18
	v_lshl_add_u64 v[18:19], v[16:17], 0, v[82:83]
	v_add_lshl_u32 v82, v135, s5, 10
	v_lshl_add_u64 v[16:17], v[16:17], 0, v[82:83]
	s_waitcnt vmcnt(3)
	ds_write2_b32 v20, v0, v1 offset1:1
	ds_write2_b32 v20, v2, v3 offset0:2 offset1:3
	s_waitcnt vmcnt(2)
	ds_write2_b32 v21, v4, v5 offset1:1
	ds_write2_b32 v21, v6, v7 offset0:2 offset1:3
	s_waitcnt vmcnt(1)
	ds_write2_b32 v29, v8, v9 offset1:1
	ds_write2_b32 v30, v10, v11 offset1:1
	s_waitcnt vmcnt(0)
	ds_write2_b32 v22, v12, v13 offset1:1
	ds_write2_b32 v22, v14, v15 offset0:2 offset1:3
	s_waitcnt lgkmcnt(0)
	s_barrier
	ds_read2_b32 v[0:1], v131 offset1:129
	ds_read2_b32 v[2:3], v23 offset0:2 offset1:131
	ds_read2_b32 v[4:5], v24 offset0:4 offset1:133
	ds_read2_b32 v[6:7], v25 offset0:6 offset1:135
	ds_read2_b32 v[8:9], v152 offset1:129
	ds_read2_b32 v[10:11], v26 offset0:2 offset1:131
	ds_read2_b32 v[12:13], v27 offset0:4 offset1:133
	ds_read2_b32 v[14:15], v28 offset0:6 offset1:135
	s_waitcnt lgkmcnt(7)
	v_cvt_pk_bf16_f32 v0, v0, v1
	s_waitcnt lgkmcnt(6)
	v_cvt_pk_bf16_f32 v1, v2, v3
	s_waitcnt lgkmcnt(5)
	v_cvt_pk_bf16_f32 v2, v4, v5
	s_waitcnt lgkmcnt(4)
	v_cvt_pk_bf16_f32 v3, v6, v7
	s_waitcnt lgkmcnt(3)
	v_cvt_pk_bf16_f32 v4, v8, v9
	s_waitcnt lgkmcnt(2)
	v_cvt_pk_bf16_f32 v5, v10, v11
	s_waitcnt lgkmcnt(1)
	v_cvt_pk_bf16_f32 v6, v12, v13
	s_waitcnt lgkmcnt(0)
	v_cvt_pk_bf16_f32 v7, v14, v15
	global_store_dwordx4 v[18:19], v[0:3], off nt
	global_store_dwordx4 v[16:17], v[4:7], off nt
	s_barrier
